# v9 + attention unit prologue: Q-load waits removed (X, A, C, D) so first K/V tile DMAs overlap the Q loads; in-order vmcnt at first tile barrier covers Q
# baseline (speedup 1.0000x reference)
; #define GASA __attribute__((address_space(1)))
; template <int DQK, int DV, bool BAND>
; DI void attn_unit(const AttnArgs& a, LAS unsigned char* lds, int tid) {
;     ...
;     { const GASA bf16_t* qrow = (const GASA bf16_t*)a.q + (long)(wid * 32 + r32) * a.qs;
; #pragma unroll
;       for (int d0 = 0; d0 < ND0; ++d0) qf[d0] = *(const GASA bf16x8*)(qrow + d0 * 16 + hi * 8); }
; #pragma unroll
;     for (int d0 = 0; d0 < ND0; ++d0) asm volatile("" : "+v"(qf[d0]));
;     asm volatile("s_waitcnt vmcnt(0)" ::: "memory");
;     int t_lo = 0, t_hi = a.kv_len >> 6;
;     if (BAND) { const int tb = (a.q0 >> 6) - 1; t_lo = tb < 0 ? 0 : tb; const int te = (a.q0 >> 6) + 5; t_hi = te < t_hi ? te : t_hi; }
;     const int qw = a.q0 + wid * 32;
;     ...
;     if (wid >= 4) __builtin_amdgcn_s_setprio(1);
.LBB0_125:
	s_ashr_i32 s40, s17, 2
	s_lshl_b32 s18, s17, 7
	s_ashr_i32 s41, s40, 31
	s_and_b32 s24, s18, 0x180
	s_lshl_b64 s[18:19], s[40:41], 18
	v_readlane_b32 s26, v255, 2
	v_readlane_b32 s27, v255, 3
	s_add_u32 s18, s26, s18
	s_addc_u32 s19, s27, s19
	s_lshl_b32 s24, s24, 1
	s_add_u32 s26, s18, s24
	v_readfirstlane_b32 s18, v177
	s_addc_u32 s27, s19, 0
	s_ashr_i32 s19, s18, 6
	s_lshl_b32 s18, s19, 5
	v_or_b32_e32 v0, s18, v182
	v_ashrrev_i32_e32 v1, 31, v0
	v_lshlrev_b64 v[0:1], 10, v[0:1]
	v_lshl_add_u64 v[0:1], s[26:27], 0, v[0:1]
	v_lshl_add_u64 v[0:1], v[0:1], 0, v[194:195]
	global_load_dwordx4 v[128:131], v[0:1], off
	global_load_dwordx4 v[132:135], v[0:1], off offset:32
	global_load_dwordx4 v[136:139], v[0:1], off offset:64
	global_load_dwordx4 v[140:143], v[0:1], off offset:96
	global_load_dwordx4 v[144:147], v[0:1], off offset:128
	global_load_dwordx4 v[148:151], v[0:1], off offset:160
	global_load_dwordx4 v[152:155], v[0:1], off offset:192
	global_load_dwordx4 v[156:159], v[0:1], off offset:224
	s_cmp_lt_i32 s19, 4
	s_nop 0
	s_nop 0
	s_nop 0
	s_nop 0
	s_nop 0
	s_nop 0
	s_nop 0
	s_nop 0
	s_nop 0
	s_cbranch_scc1 .LBB0_127
	s_setprio 1

; #define GASA __attribute__((address_space(1)))
; template <int DQK, int DV, bool BAND>
; DI void attn_unit(const AttnArgs& a, LAS unsigned char* lds, int tid) {
;     ...
;     { const GASA bf16_t* qrow = (const GASA bf16_t*)a.q + (long)(wid * 32 + r32) * a.qs;
; #pragma unroll
;       for (int d0 = 0; d0 < ND0; ++d0) qf[d0] = *(const GASA bf16x8*)(qrow + d0 * 16 + hi * 8); }
; #pragma unroll
;     for (int d0 = 0; d0 < ND0; ++d0) asm volatile("" : "+v"(qf[d0]));
;     asm volatile("s_waitcnt vmcnt(0)" ::: "memory");
; __global__ void __launch_bounds__(512, 2) mega_fwd(Params p) {
;     ...
;                         for (int u = vcu; u < nunits; u += G) {
;                             int r = u; const int qb = r % nqb; r /= nqb; const int h = r % 16; const int sq = r / 16;
;                             const size_t row0 = (size_t)sq * S;
;                             AttnArgs a; a.nomax = 0; a.q = QD + (row0 + qb * 256) * 1536 + h * 96; a.qs = 1536; a.k = KVD + row0 * 2048 + h * 128; a.ks = 2048; a.k2 = KR + row0 * 32; a.k2s = 32;
;                             a.v = KVD + row0 * 2048 + h * 128 + 64; a.vs = 2048; a.o = AO + (row0 + qb * 256) * 1024 + h * 64; a.os = 1024; a.lse = nullptr; a.lses = 0;
;                             a.kv_len = S; a.q0 = qb * 256;
;                             attn_unit<96, 64, false>(a, lds, tid);
.LBB0_168:
	s_ashr_i32 s24, s26, 31
	v_readlane_b32 s27, v254, 31
	s_xor_b32 s24, s24, s27
	s_abs_i32 s27, s26
	v_readlane_b32 s34, v254, 33
	s_mul_hi_u32 s34, s27, s34
	v_readlane_b32 s41, v254, 32
	s_mul_i32 s35, s34, s41
	s_sub_i32 s27, s27, s35
	s_add_i32 s35, s34, 1
	s_sub_i32 s40, s27, s41
	s_cmp_ge_u32 s27, s41
	s_cselect_b32 s34, s35, s34
	s_cselect_b32 s27, s40, s27
	s_add_i32 s35, s34, 1
	s_cmp_ge_u32 s27, s41
	s_cselect_b32 s27, s35, s34
	s_xor_b32 s27, s27, s24
	s_sub_i32 s24, s27, s24
	s_ashr_i32 s34, s24, 31
	s_lshr_b32 s34, s34, 28
	v_readlane_b32 s27, v254, 30
	s_add_i32 s34, s24, s34
	s_mul_i32 s27, s24, s27
	s_ashr_i32 s40, s34, 4
	s_and_b32 s34, s34, -16
	s_sub_i32 s27, s26, s27
	s_sub_i32 s34, s24, s34
	s_ashr_i32 s41, s40, 31
	v_readlane_b32 s24, v254, 22
	s_lshl_b64 s[40:41], s[40:41], s24
	s_lshl_b32 s24, s27, 8
	s_ashr_i32 s27, s24, 31
	s_add_u32 s42, s40, s24
	s_addc_u32 s43, s41, s27
	s_mul_i32 s24, s43, 0xc00
	s_mul_hi_u32 s27, s42, 0xc00
	s_add_i32 s27, s27, s24
	s_mul_i32 s24, s42, 0xc00
	s_add_u32 s24, s16, s24
	s_mul_i32 s44, s34, 0x60
	s_addc_u32 s27, s17, s27
	s_ashr_i32 s45, s44, 31
	s_lshl_b64 s[44:45], s[44:45], 1
	s_add_u32 s44, s24, s44
	v_readfirstlane_b32 s52, v177
	s_addc_u32 s45, s27, s45
	s_ashr_i32 s35, s52, 6
	s_lshl_b32 s27, s35, 5
	v_or_b32_e32 v2, s27, v157
	v_mov_b64_e32 v[0:1], s[44:45]
	v_mad_i64_i32 v[0:1], s[44:45], v2, s95, v[0:1]
	v_mov_b32_e32 v171, v195
	v_lshl_add_u64 v[0:1], v[0:1], 0, v[170:171]
	global_load_dwordx4 v[96:99], v[0:1], off
	global_load_dwordx4 v[100:103], v[0:1], off offset:32
	global_load_dwordx4 v[104:107], v[0:1], off offset:64
	global_load_dwordx4 v[108:111], v[0:1], off offset:96
	global_load_dwordx4 v[112:115], v[0:1], off offset:128
	global_load_dwordx4 v[116:119], v[0:1], off offset:160
	s_cmp_lt_i32 s35, 4
	s_nop 0
	s_nop 0
	s_nop 0
	s_nop 0
	s_nop 0
	s_nop 0
	s_nop 0
	s_cbranch_scc1 .LBB0_170
	s_setprio 1

; #define GASA __attribute__((address_space(1)))
; template <int DQK, int DV, bool BAND>
; DI void attn_unit(const AttnArgs& a, LAS unsigned char* lds, int tid) {
;     ...
;     { const GASA bf16_t* qrow = (const GASA bf16_t*)a.q + (long)(wid * 32 + r32) * a.qs;
; #pragma unroll
;       for (int d0 = 0; d0 < ND0; ++d0) qf[d0] = *(const GASA bf16x8*)(qrow + d0 * 16 + hi * 8); }
; #pragma unroll
;     for (int d0 = 0; d0 < ND0; ++d0) asm volatile("" : "+v"(qf[d0]));
;     asm volatile("s_waitcnt vmcnt(0)" ::: "memory");
; __global__ void __launch_bounds__(512, 2) mega_fwd(Params p) {
;     ...
;                         for (int u = vcu; u < nunits; u += G) {
;                             int r = u; const int qb = r % nqb; r /= nqb; const int hc = r % 16; const int sq = r / 16;
;                             const size_t row0 = (size_t)sq * S;
;                             AttnArgs a; a.nomax = 0; a.q = BIG + (row0 + qb * 256) * 3072 + hc * 64; a.qs = 3072; a.k = BIG + row0 * 3072 + 1024 + hc * 64; a.ks = 3072; a.k2 = nullptr; a.k2s = 0;
;                             a.v = BIG + row0 * 3072 + 2048 + (hc >> 1) * 128; a.vs = 3072; a.o = OC + (row0 + qb * 256) * 2048 + hc * 128; a.os = 2048; a.lse = nullptr; a.lses = 0;
;                             a.kv_len = S; a.q0 = qb * 256;
;                             attn_unit<64, 128, false>(a, lds, tid);
.LBB0_208:
	s_ashr_i32 s17, s16, 31
	v_readlane_b32 s18, v254, 31
	s_xor_b32 s17, s17, s18
	s_abs_i32 s18, s16
	v_readlane_b32 s19, v254, 33
	s_mul_hi_u32 s19, s18, s19
	v_readlane_b32 s27, v254, 32
	s_mul_i32 s24, s19, s27
	s_sub_i32 s18, s18, s24
	s_add_i32 s24, s19, 1
	s_sub_i32 s26, s18, s27
	s_cmp_ge_u32 s18, s27
	s_cselect_b32 s19, s24, s19
	s_cselect_b32 s18, s26, s18
	s_add_i32 s24, s19, 1
	s_cmp_ge_u32 s18, s27
	s_cselect_b32 s18, s24, s19
	s_xor_b32 s18, s18, s17
	s_sub_i32 s17, s18, s17
	v_readlane_b32 s18, v254, 30
	s_mul_i32 s18, s17, s18
	s_sub_i32 s19, s16, s18
	s_ashr_i32 s18, s17, 31
	s_lshr_b32 s18, s18, 28
	s_add_i32 s18, s17, s18
	s_ashr_i32 s26, s18, 4
	s_and_b32 s18, s18, -16
	s_sub_i32 s18, s17, s18
	s_ashr_i32 s27, s26, 31
	v_readlane_b32 s17, v254, 22
	s_lshl_b64 s[46:47], s[26:27], s17
	s_lshl_b32 s17, s19, 8
	s_ashr_i32 s19, s17, 31
	s_add_u32 s42, s46, s17
	s_addc_u32 s43, s47, s19
	s_mul_i32 s17, s43, 0x1800
	s_mul_hi_u32 s19, s42, 0x1800
	s_add_i32 s19, s19, s17
	s_mul_i32 s17, s42, 0x1800
	s_add_u32 s17, s70, s17
	s_addc_u32 s19, s71, s19
	s_lshl_b32 s48, s18, 6
	s_ashr_i32 s49, s48, 31
	s_lshl_b64 s[40:41], s[48:49], 1
	s_add_u32 s26, s17, s40
	v_readfirstlane_b32 s17, v177
	s_addc_u32 s27, s19, s41
	s_ashr_i32 s19, s17, 6
	s_lshl_b32 s17, s19, 5
	v_or_b32_e32 v2, s17, v196
	v_mov_b64_e32 v[0:1], s[26:27]
	s_movk_i32 s24, 0x1800
	v_mad_i64_i32 v[0:1], s[26:27], v2, s24, v[0:1]
	v_lshl_add_u64 v[0:1], v[0:1], 0, v[194:195]
	global_load_dwordx4 v[128:131], v[0:1], off
	global_load_dwordx4 v[132:135], v[0:1], off offset:32
	global_load_dwordx4 v[136:139], v[0:1], off offset:64
	global_load_dwordx4 v[140:143], v[0:1], off offset:96
	s_cmp_lt_i32 s19, 4
	s_nop 0
	s_nop 0
	s_nop 0
	s_nop 0
	s_nop 0
	s_cbranch_scc1 .LBB0_210
	s_setprio 1

; #define GASA __attribute__((address_space(1)))
; template <int DQK, int DV, bool BAND>
; DI void attn_unit(const AttnArgs& a, LAS unsigned char* lds, int tid) {
;     ...
;     { const GASA bf16_t* qrow = (const GASA bf16_t*)a.q + (long)(wid * 32 + r32) * a.qs;
; #pragma unroll
;       for (int d0 = 0; d0 < ND0; ++d0) qf[d0] = *(const GASA bf16x8*)(qrow + d0 * 16 + hi * 8); }
; #pragma unroll
;     for (int d0 = 0; d0 < ND0; ++d0) asm volatile("" : "+v"(qf[d0]));
;     asm volatile("s_waitcnt vmcnt(0)" ::: "memory");
; __global__ void __launch_bounds__(512, 2) mega_fwd(Params p) {
;     ...
;                         for (int u = vcu; u < nunits; u += G) {
;                             int r = u; const int qb = r % nqb; r /= nqb; const int h = r % 8; r /= 8; const int g = r % 3; const int sq = r / 3;
;                             const int dil = g == 0 ? 1 : (g == 1 ? 4 : 16); const int L = S / dil, bpr = L / 256;
;                             const int res = qb / bpr, q0 = (qb % bpr) * 256;
;                             bf16_t* base = BIG + ((size_t)sq * S + res) * 4608 + g * 1536 + h * 64;
;                             AttnArgs a; a.nomax = 0; a.q = base + (size_t)q0 * dil * 4608; a.qs = (long)dil * 4608; a.k = base + 512; a.ks = a.qs; a.k2 = nullptr; a.k2s = 0; a.v = base + 1024; a.vs = a.qs;
;                             a.o = base + (size_t)q0 * dil * 4608; a.os = a.qs; a.lse = LSE + ((size_t)g * TC + (size_t)sq * S + res + (size_t)q0 * dil) * 8 + h; a.lses = (long)dil * 8;
;                             a.kv_len = L; a.q0 = q0;
;                             attn_unit<64, 64, true>(a, lds, tid);
.LBB0_266:
	s_ashr_i32 s17, s16, 31
	v_readlane_b32 s18, v254, 31
	s_xor_b32 s17, s17, s18
	s_abs_i32 s18, s16
	v_readlane_b32 s19, v254, 33
	s_mul_hi_u32 s19, s18, s19
	v_readlane_b32 s27, v254, 32
	s_mul_i32 s24, s19, s27
	s_sub_i32 s18, s18, s24
	s_add_i32 s24, s19, 1
	s_sub_i32 s26, s18, s27
	s_cmp_ge_u32 s18, s27
	s_cselect_b32 s19, s24, s19
	s_cselect_b32 s18, s26, s18
	s_add_i32 s24, s19, 1
	s_cmp_ge_u32 s18, s27
	s_cselect_b32 s18, s24, s19
	s_xor_b32 s18, s18, s17
	s_sub_i32 s17, s18, s17
	v_readlane_b32 s18, v254, 30
	s_mul_i32 s18, s17, s18
	s_sub_i32 s19, s16, s18
	s_ashr_i32 s18, s17, 31
	s_lshr_b32 s18, s18, 29
	s_add_i32 s18, s17, s18
	s_ashr_i32 s24, s18, 3
	s_and_b32 s18, s18, -8
	s_sub_i32 s50, s17, s18
	s_mul_hi_i32 s18, s24, 0x55555556
	s_lshr_b32 s26, s18, 31
	s_add_i32 s18, s18, s26
	s_mul_i32 s18, s18, 3
	s_mul_hi_i32 s17, s17, 0x2aaaaaab
	s_sub_i32 s52, s24, s18
	s_lshr_b32 s18, s17, 31
	s_ashr_i32 s17, s17, 2
	s_add_i32 s18, s17, s18
	s_cmp_eq_u32 s52, 0
	s_cselect_b64 s[42:43], -1, 0
	s_cmp_eq_u32 s52, 1
	s_cselect_b64 s[48:49], -1, 0
	s_and_b64 s[26:27], s[48:49], exec
	s_cselect_b32 s17, 2, 4
	s_and_b64 s[26:27], s[42:43], exec
	s_cselect_b32 s17, 0, s17
	s_lshr_b32 s24, s56, s17
	s_lshr_b32 s26, s24, 8
	s_abs_i32 s27, s26
	v_cvt_f32_u32_e32 v0, s27
	s_sub_i32 s36, 0, s27
	s_abs_i32 s35, s19
	s_xor_b32 s34, s19, s26
	v_rcp_iflag_f32_e32 v0, v0
	s_ashr_i32 s34, s34, 31
	v_mul_f32_e32 v0, 0x4f7ffffe, v0
	v_cvt_u32_f32_e32 v0, v0
	s_nop 0
	v_readfirstlane_b32 s37, v0
	s_mul_i32 s36, s36, s37
	s_mul_hi_u32 s36, s37, s36
	s_add_i32 s37, s37, s36
	s_mul_hi_u32 s36, s35, s37
	s_mul_i32 s37, s36, s27
	s_sub_i32 s35, s35, s37
	s_add_i32 s37, s36, 1
	s_sub_i32 s40, s35, s27
	s_cmp_ge_u32 s35, s27
	s_cselect_b32 s36, s37, s36
	s_cselect_b32 s35, s40, s35
	s_add_i32 s37, s36, 1
	s_cmp_ge_u32 s35, s27
	s_cselect_b32 s27, s37, s36
	s_xor_b32 s27, s27, s34
	s_sub_i32 s27, s27, s34
	s_mul_i32 s26, s27, s26
	s_sub_i32 s34, s19, s26
	s_ashr_i32 s19, s18, 31
	v_readlane_b32 s26, v254, 22
	s_lshl_b32 s40, s34, 8
	s_lshl_b64 s[18:19], s[18:19], s26
	s_ashr_i32 s35, s27, 31
	s_add_u32 s26, s18, s27
	s_addc_u32 s27, s19, s35
	s_mul_i32 s18, s27, 0x2400
	s_mul_hi_u32 s19, s26, 0x2400
	s_add_i32 s51, s19, s18
	s_mul_i32 s53, s26, 0x2400
	s_add_u32 s35, s70, s53
	s_mul_i32 s18, s52, 0x600
	s_addc_u32 s36, s71, s51
	s_ashr_i32 s19, s18, 31
	s_lshl_b64 s[46:47], s[18:19], 1
	s_add_u32 s35, s35, s46
	s_addc_u32 s36, s36, s47
	s_lshl_b32 s18, s50, 6
	s_ashr_i32 s19, s18, 31
	s_lshl_b64 s[64:65], s[18:19], 1
	s_add_u32 s18, s35, s64
	s_addc_u32 s19, s36, s65
	s_ashr_i32 s41, s40, 31
	s_lshl_b64 s[54:55], s[40:41], s17
	s_mul_i32 s17, s55, 0x2400
	s_mul_hi_u32 s35, s54, 0x2400
	s_add_i32 s35, s35, s17
	s_mul_i32 s17, s54, 0x2400
	s_add_u32 s36, s18, s17
	s_addc_u32 s37, s19, s35
	s_and_b64 s[18:19], s[48:49], exec
	s_movk_i32 s17, 0x4800
	s_cselect_b32 s17, s17, 0x12000
	s_and_b64 s[18:19], s[42:43], exec
	v_readfirstlane_b32 s41, v177
	s_cselect_b32 s17, 0x1200, s17
	s_ashr_i32 s19, s41, 6
	s_lshl_b32 s18, s19, 5
	v_or_b32_e32 v0, s18, v168
	v_mad_i64_i32 v[0:1], s[56:57], s17, v0, 0
	v_lshl_add_u64 v[0:1], v[0:1], 1, s[36:37]
	v_lshl_add_u64 v[0:1], v[0:1], 0, v[194:195]
	global_load_dwordx4 v[116:119], v[0:1], off
	global_load_dwordx4 v[120:123], v[0:1], off offset:32
	global_load_dwordx4 v[124:127], v[0:1], off offset:64
	global_load_dwordx4 v[128:131], v[0:1], off offset:96
	s_cmp_lt_i32 s19, 4
	s_nop 0
	s_nop 0
	s_nop 0
	s_nop 0
	s_nop 0
	s_cbranch_scc1 .LBB0_268
	s_setprio 1
